# write-through (sc1) stores also for the gate logits (P1) and the bf16 residual copy (P4/P6 epilogues)
# baseline (speedup 1.0000x reference)
.LBB0_195:
	s_and_b64 vcc, exec, s[6:7]
	s_cbranch_vccz .LBB0_290
	s_lshl_b32 s6, s58, 6
	s_lshl_b32 s7, s25, 2
	s_add_i32 s6, s6, s7
	s_add_i32 s34, s6, 0xffffffb4
	s_ashr_i32 s35, s34, 31
	s_lshl_b64 s[34:35], s[34:35], 15
	s_add_u32 s34, s27, s34
	v_pk_mul_f32 v[126:127], v[126:127], v[156:157] op_sel_hi:[1,0]
	s_addc_u32 s35, s82, s35
	v_pk_mul_f32 v[130:131], v[124:125], v[156:157] op_sel_hi:[1,0]
	v_pk_mul_f32 v[124:125], v[122:123], v[156:157] op_sel_hi:[1,0]
	v_cvt_pk_bf16_f32 v122, v126, v127
	v_lshl_add_u64 v[126:127], s[34:35], 0, v[154:155]
	s_add_i32 s34, s6, 0xffffffb6
	s_ashr_i32 s35, s34, 31
	v_pk_mul_f32 v[128:129], v[128:129], v[156:157] op_sel_hi:[1,0]
	s_lshl_b64 s[34:35], s[34:35], 15
	v_cvt_pk_bf16_f32 v123, v128, v129
	v_cvt_pk_bf16_f32 v124, v124, v125
	v_cvt_pk_bf16_f32 v125, v130, v131
	s_add_u32 s34, s27, s34
	global_store_dwordx4 v[126:127], v[122:125], off sc1
	v_pk_mul_f32 v[120:121], v[120:121], v[156:157] op_sel_hi:[1,0]
	v_pk_mul_f32 v[118:119], v[118:119], v[156:157] op_sel_hi:[1,0]
	v_pk_mul_f32 v[122:123], v[116:117], v[156:157] op_sel_hi:[1,0]
	v_pk_mul_f32 v[116:117], v[114:115], v[156:157] op_sel_hi:[1,0]
	s_addc_u32 s35, s82, s35
	v_cvt_pk_bf16_f32 v114, v118, v119
	v_cvt_pk_bf16_f32 v115, v120, v121
	v_cvt_pk_bf16_f32 v116, v116, v117
	v_cvt_pk_bf16_f32 v117, v122, v123
	v_lshl_add_u64 v[118:119], s[34:35], 0, v[154:155]
	v_pk_mul_f32 v[110:111], v[110:111], v[158:159] op_sel_hi:[1,0]
	global_store_dwordx4 v[118:119], v[114:117], off sc1
	v_pk_mul_f32 v[112:113], v[112:113], v[158:159] op_sel_hi:[1,0]
	v_pk_mul_f32 v[102:103], v[102:103], v[158:159] op_sel_hi:[1,0]
	v_pk_mul_f32 v[114:115], v[108:109], v[158:159] op_sel_hi:[1,0]
	v_pk_mul_f32 v[108:109], v[106:107], v[158:159] op_sel_hi:[1,0]
	v_cvt_pk_bf16_f32 v106, v110, v111
	v_add_co_u32_e32 v110, vcc, s36, v126
	v_cvt_pk_bf16_f32 v107, v112, v113
	v_cvt_pk_bf16_f32 v108, v108, v109
	v_cvt_pk_bf16_f32 v109, v114, v115
	v_addc_co_u32_e32 v111, vcc, 0, v127, vcc
	global_store_dwordx4 v[110:111], v[106:109], off sc1
	v_pk_mul_f32 v[104:105], v[104:105], v[158:159] op_sel_hi:[1,0]
	v_pk_mul_f32 v[94:95], v[94:95], v[160:161] op_sel_hi:[1,0]
	v_pk_mul_f32 v[106:107], v[100:101], v[158:159] op_sel_hi:[1,0]
	v_pk_mul_f32 v[100:101], v[98:99], v[158:159] op_sel_hi:[1,0]
	v_cvt_pk_bf16_f32 v98, v102, v103
	v_add_co_u32_e32 v102, vcc, s36, v118
	v_cvt_pk_bf16_f32 v99, v104, v105
	v_cvt_pk_bf16_f32 v100, v100, v101
	v_cvt_pk_bf16_f32 v101, v106, v107
	v_addc_co_u32_e32 v103, vcc, 0, v119, vcc
	global_store_dwordx4 v[102:103], v[98:101], off sc1
	v_pk_mul_f32 v[96:97], v[96:97], v[160:161] op_sel_hi:[1,0]
	v_pk_mul_f32 v[86:87], v[86:87], v[160:161] op_sel_hi:[1,0]
	v_pk_mul_f32 v[98:99], v[92:93], v[160:161] op_sel_hi:[1,0]
	v_pk_mul_f32 v[92:93], v[90:91], v[160:161] op_sel_hi:[1,0]
	v_cvt_pk_bf16_f32 v90, v94, v95
	v_add_co_u32_e32 v94, vcc, s37, v126
	v_cvt_pk_bf16_f32 v91, v96, v97
	v_cvt_pk_bf16_f32 v92, v92, v93
	v_cvt_pk_bf16_f32 v93, v98, v99
	v_addc_co_u32_e32 v95, vcc, 0, v127, vcc
	global_store_dwordx4 v[94:95], v[90:93], off sc1
	v_pk_mul_f32 v[88:89], v[88:89], v[160:161] op_sel_hi:[1,0]
	s_add_i32 s34, s6, 0xffffffb5
	v_pk_mul_f32 v[90:91], v[84:85], v[160:161] op_sel_hi:[1,0]
	v_pk_mul_f32 v[84:85], v[82:83], v[160:161] op_sel_hi:[1,0]
	v_cvt_pk_bf16_f32 v82, v86, v87
	v_add_co_u32_e32 v86, vcc, s37, v118
	v_cvt_pk_bf16_f32 v83, v88, v89
	v_cvt_pk_bf16_f32 v84, v84, v85
	v_cvt_pk_bf16_f32 v85, v90, v91
	v_addc_co_u32_e32 v87, vcc, 0, v119, vcc
	v_pk_mul_f32 v[78:79], v[78:79], v[162:163] op_sel_hi:[1,0]
	s_movk_i32 s25, 0x6000
	s_ashr_i32 s35, s34, 31
	global_store_dwordx4 v[86:87], v[82:85], off sc1
	v_pk_mul_f32 v[80:81], v[80:81], v[162:163] op_sel_hi:[1,0]
	s_lshl_b64 s[34:35], s[34:35], 15
	v_pk_mul_f32 v[82:83], v[76:77], v[162:163] op_sel_hi:[1,0]
	v_pk_mul_f32 v[76:77], v[74:75], v[162:163] op_sel_hi:[1,0]
	v_cvt_pk_bf16_f32 v74, v78, v79
	v_add_co_u32_e32 v78, vcc, s25, v126
	v_cvt_pk_bf16_f32 v75, v80, v81
	v_cvt_pk_bf16_f32 v76, v76, v77
	v_cvt_pk_bf16_f32 v77, v82, v83
	v_addc_co_u32_e32 v79, vcc, 0, v127, vcc
	v_pk_mul_f32 v[70:71], v[70:71], v[162:163] op_sel_hi:[1,0]
	s_add_u32 s34, s27, s34
	global_store_dwordx4 v[78:79], v[74:77], off sc1
	v_pk_mul_f32 v[72:73], v[72:73], v[162:163] op_sel_hi:[1,0]
	s_addc_u32 s35, s82, s35
	v_pk_mul_f32 v[74:75], v[68:69], v[162:163] op_sel_hi:[1,0]
	v_pk_mul_f32 v[68:69], v[66:67], v[162:163] op_sel_hi:[1,0]
	v_cvt_pk_bf16_f32 v66, v70, v71
	v_add_co_u32_e32 v70, vcc, s25, v118
	s_addk_i32 s6, 0xffb7
	v_cvt_pk_bf16_f32 v67, v72, v73
	v_cvt_pk_bf16_f32 v68, v68, v69
	v_cvt_pk_bf16_f32 v69, v74, v75
	v_addc_co_u32_e32 v71, vcc, 0, v119, vcc
	s_ashr_i32 s7, s6, 31
	global_store_dwordx4 v[70:71], v[66:69], off sc1
	v_pk_mul_f32 v[64:65], v[64:65], v[164:165] op_sel_hi:[1,0]
	v_pk_mul_f32 v[62:63], v[62:63], v[164:165] op_sel_hi:[1,0]
	v_pk_mul_f32 v[66:67], v[60:61], v[164:165] op_sel_hi:[1,0]
	v_pk_mul_f32 v[60:61], v[58:59], v[164:165] op_sel_hi:[1,0]
	s_lshl_b64 s[6:7], s[6:7], 15
	v_cvt_pk_bf16_f32 v58, v62, v63
	v_cvt_pk_bf16_f32 v59, v64, v65
	v_cvt_pk_bf16_f32 v60, v60, v61
	v_cvt_pk_bf16_f32 v61, v66, v67
	v_lshl_add_u64 v[62:63], s[34:35], 0, v[154:155]
	s_add_u32 s6, s27, s6
	global_store_dwordx4 v[62:63], v[58:61], off sc1
	v_pk_mul_f32 v[56:57], v[56:57], v[164:165] op_sel_hi:[1,0]
	v_pk_mul_f32 v[54:55], v[54:55], v[164:165] op_sel_hi:[1,0]
	v_pk_mul_f32 v[58:59], v[52:53], v[164:165] op_sel_hi:[1,0]
	v_pk_mul_f32 v[52:53], v[50:51], v[164:165] op_sel_hi:[1,0]
	s_addc_u32 s7, s82, s7
	v_cvt_pk_bf16_f32 v50, v54, v55
	v_cvt_pk_bf16_f32 v51, v56, v57
	v_cvt_pk_bf16_f32 v52, v52, v53
	v_cvt_pk_bf16_f32 v53, v58, v59
	v_lshl_add_u64 v[54:55], s[6:7], 0, v[154:155]
	v_pk_mul_f32 v[46:47], v[46:47], v[166:167] op_sel_hi:[1,0]
	global_store_dwordx4 v[54:55], v[50:53], off sc1
	v_pk_mul_f32 v[48:49], v[48:49], v[166:167] op_sel_hi:[1,0]
	v_pk_mul_f32 v[38:39], v[38:39], v[166:167] op_sel_hi:[1,0]
	v_pk_mul_f32 v[50:51], v[44:45], v[166:167] op_sel_hi:[1,0]
	v_pk_mul_f32 v[44:45], v[42:43], v[166:167] op_sel_hi:[1,0]
	v_cvt_pk_bf16_f32 v42, v46, v47
	v_add_co_u32_e32 v46, vcc, s36, v62
	v_cvt_pk_bf16_f32 v43, v48, v49
	v_cvt_pk_bf16_f32 v44, v44, v45
	v_cvt_pk_bf16_f32 v45, v50, v51
	v_addc_co_u32_e32 v47, vcc, 0, v63, vcc
	global_store_dwordx4 v[46:47], v[42:45], off sc1
	v_pk_mul_f32 v[40:41], v[40:41], v[166:167] op_sel_hi:[1,0]
	v_pk_mul_f32 v[30:31], v[30:31], v[168:169] op_sel_hi:[1,0]
	v_pk_mul_f32 v[42:43], v[36:37], v[166:167] op_sel_hi:[1,0]
	v_pk_mul_f32 v[36:37], v[34:35], v[166:167] op_sel_hi:[1,0]
	v_cvt_pk_bf16_f32 v34, v38, v39
	v_add_co_u32_e32 v38, vcc, s36, v54
	v_cvt_pk_bf16_f32 v35, v40, v41
	v_cvt_pk_bf16_f32 v36, v36, v37
	v_cvt_pk_bf16_f32 v37, v42, v43
	v_addc_co_u32_e32 v39, vcc, 0, v55, vcc
	global_store_dwordx4 v[38:39], v[34:37], off sc1
	v_pk_mul_f32 v[32:33], v[32:33], v[168:169] op_sel_hi:[1,0]
	v_pk_mul_f32 v[22:23], v[22:23], v[168:169] op_sel_hi:[1,0]
	v_pk_mul_f32 v[34:35], v[28:29], v[168:169] op_sel_hi:[1,0]
	v_pk_mul_f32 v[28:29], v[26:27], v[168:169] op_sel_hi:[1,0]
	v_cvt_pk_bf16_f32 v26, v30, v31
	v_add_co_u32_e32 v30, vcc, s37, v62
	v_cvt_pk_bf16_f32 v27, v32, v33
	v_cvt_pk_bf16_f32 v28, v28, v29
	v_cvt_pk_bf16_f32 v29, v34, v35
	v_addc_co_u32_e32 v31, vcc, 0, v63, vcc
	global_store_dwordx4 v[30:31], v[26:29], off sc1
	v_pk_mul_f32 v[24:25], v[24:25], v[168:169] op_sel_hi:[1,0]
	v_pk_mul_f32 v[14:15], v[14:15], v[170:171] op_sel_hi:[1,0]
	v_pk_mul_f32 v[26:27], v[20:21], v[168:169] op_sel_hi:[1,0]
	v_pk_mul_f32 v[20:21], v[18:19], v[168:169] op_sel_hi:[1,0]
	v_cvt_pk_bf16_f32 v18, v22, v23
	v_add_co_u32_e32 v22, vcc, s37, v54
	v_cvt_pk_bf16_f32 v19, v24, v25
	v_cvt_pk_bf16_f32 v20, v20, v21
	v_cvt_pk_bf16_f32 v21, v26, v27
	v_addc_co_u32_e32 v23, vcc, 0, v55, vcc
	global_store_dwordx4 v[22:23], v[18:21], off sc1
	v_pk_mul_f32 v[16:17], v[16:17], v[170:171] op_sel_hi:[1,0]
	v_pk_mul_f32 v[6:7], v[6:7], v[170:171] op_sel_hi:[1,0]
	v_pk_mul_f32 v[18:19], v[12:13], v[170:171] op_sel_hi:[1,0]
	v_pk_mul_f32 v[12:13], v[10:11], v[170:171] op_sel_hi:[1,0]
	v_cvt_pk_bf16_f32 v10, v14, v15
	v_add_co_u32_e32 v14, vcc, s25, v62
	v_cvt_pk_bf16_f32 v11, v16, v17
	v_cvt_pk_bf16_f32 v12, v12, v13
	v_cvt_pk_bf16_f32 v13, v18, v19
	v_addc_co_u32_e32 v15, vcc, 0, v63, vcc
	global_store_dwordx4 v[14:15], v[10:13], off sc1
	v_pk_mul_f32 v[8:9], v[8:9], v[170:171] op_sel_hi:[1,0]
	s_nop 0
	v_pk_mul_f32 v[10:11], v[4:5], v[170:171] op_sel_hi:[1,0]
	v_pk_mul_f32 v[4:5], v[2:3], v[170:171] op_sel_hi:[1,0]
	v_cvt_pk_bf16_f32 v2, v6, v7
	v_add_co_u32_e32 v6, vcc, 0x6000, v54
	v_cvt_pk_bf16_f32 v3, v8, v9
	v_cvt_pk_bf16_f32 v4, v4, v5
	v_cvt_pk_bf16_f32 v5, v10, v11
	v_addc_co_u32_e32 v7, vcc, 0, v55, vcc
	global_store_dwordx4 v[6:7], v[2:5], off sc1
	s_andn2_b64 vcc, exec, s[4:5]
	s_mov_b64 s[4:5], -1
	s_cbranch_vccnz .LBB0_172
	s_branch .LBB0_291

.LBB0_791:
	s_mov_b32 s8, s77
	s_lshl_b32 s8, s59, 2
	v_lshl_add_u32 v142, s58, 8, v148
	v_lshl_or_b32 v140, s59, 8, v150
	v_ashrrev_i32_e32 v143, 31, v142
	v_lshlrev_b64 v[152:153], 12, v[142:143]
	v_ashrrev_i32_e32 v141, 31, v140
	v_lshl_add_u64 v[146:147], s[12:13], 0, v[152:153]
	v_lshlrev_b64 v[144:145], 2, v[140:141]
	s_waitcnt lgkmcnt(0)
	v_lshl_add_u64 v[152:153], s[0:1], 0, v[152:153]
	v_lshl_add_u64 v[160:161], v[152:153], 0, v[144:145]
	global_load_dwordx4 v[152:155], v[160:161], off offset:16
	global_load_dwordx4 v[156:159], v[160:161], off
	v_lshl_add_u64 v[146:147], v[146:147], 0, v[144:145]
	s_ashr_i32 s9, s8, 31
	s_waitcnt vmcnt(0)
	v_pk_add_f32 v[124:125], v[124:125], v[154:155]
	v_pk_add_f32 v[128:129], v[128:129], v[158:159]
	v_pk_add_f32 v[126:127], v[126:127], v[156:157]
	v_pk_add_f32 v[122:123], v[122:123], v[152:153]
	global_store_dwordx4 v[146:147], v[126:129], off
	global_store_dwordx4 v[146:147], v[122:125], off offset:16
	v_cvt_pk_bf16_f32 v152, v126, v127
	v_mul_f32_e32 v127, v127, v127
	v_fmac_f32_e32 v127, v126, v126
	v_mul_f32_e32 v126, v129, v129
	v_cvt_pk_bf16_f32 v154, v122, v123
	v_lshlrev_b64 v[156:157], 11, v[142:143]
	v_fmac_f32_e32 v126, v128, v128
	v_mul_f32_e32 v123, v123, v123
	v_lshl_add_u64 v[156:157], s[16:17], 0, v[156:157]
	v_add_f32_e32 v126, v127, v126
	v_fmac_f32_e32 v123, v122, v122
	v_cvt_pk_bf16_f32 v153, v128, v129
	v_cvt_pk_bf16_f32 v155, v124, v125
	v_lshl_add_u64 v[156:157], v[140:141], 1, v[156:157]
	v_add_f32_e32 v122, v126, v123
	v_mul_f32_e32 v123, v125, v125
	global_store_dwordx4 v[156:157], v[152:155], off sc1
	v_fmac_f32_e32 v123, v124, v124
	s_nop 0
	v_add_f32_e32 v152, v123, v122
	global_load_dwordx4 v[122:125], v[160:161], off offset:528
	global_load_dwordx4 v[126:129], v[160:161], off offset:512
	s_waitcnt vmcnt(1)
	v_pk_add_f32 v[116:117], v[116:117], v[124:125]
	s_waitcnt vmcnt(0)
	v_pk_add_f32 v[120:121], v[120:121], v[128:129]
	v_pk_add_f32 v[118:119], v[118:119], v[126:127]
	v_pk_add_f32 v[114:115], v[114:115], v[122:123]
	global_store_dwordx4 v[146:147], v[118:121], off offset:512
	global_store_dwordx4 v[146:147], v[114:117], off offset:528
	v_cvt_pk_bf16_f32 v122, v118, v119
	v_mul_f32_e32 v119, v119, v119
	v_fmac_f32_e32 v119, v118, v118
	v_mul_f32_e32 v118, v121, v121
	v_cvt_pk_bf16_f32 v124, v114, v115
	v_fmac_f32_e32 v118, v120, v120
	v_mul_f32_e32 v115, v115, v115
	v_add_f32_e32 v118, v119, v118
	v_fmac_f32_e32 v115, v114, v114
	v_add_f32_e32 v114, v118, v115
	v_mul_f32_e32 v115, v117, v117
	v_fmac_f32_e32 v115, v116, v116
	v_add_f32_e32 v114, v115, v114
	v_add_f32_e32 v114, v152, v114
	ds_swizzle_b32 v115, v114 offset:swizzle(SWAP,16)
	v_cvt_pk_bf16_f32 v123, v120, v121
	v_cvt_pk_bf16_f32 v125, v116, v117
	global_store_dwordx4 v[156:157], v[122:125], off offset:256 sc1
	s_waitcnt lgkmcnt(0)
	v_add_f32_e32 v114, v114, v115
	v_mov_b32_e32 v115, v114
	s_nop 1
	v_permlane32_swap_b32_e32 v114, v115
	s_and_saveexec_b64 s[34:35], s[4:5]
	s_cbranch_execz .LBB0_793
	v_lshlrev_b64 v[116:117], 6, v[142:143]
	v_lshl_add_u64 v[116:117], s[14:15], 0, v[116:117]
	v_lshl_add_u64 v[116:117], s[8:9], 2, v[116:117]
	s_lshl_b32 s76, s65, 2
	v_lshl_add_u64 v[116:117], v[116:117], 0, s[76:77]
	v_add_f32_e32 v114, v114, v115
	global_store_dword v[116:117], v114, off
.LBB0_793:
	s_or_b64 exec, exec, s[34:35]
	v_or_b32_e32 v114, 16, v142
	v_ashrrev_i32_e32 v115, 31, v114
	v_lshlrev_b64 v[118:119], 12, v[114:115]
	v_lshl_add_u64 v[116:117], s[12:13], 0, v[118:119]
	v_lshl_add_u64 v[118:119], s[0:1], 0, v[118:119]
	v_lshl_add_u64 v[126:127], v[118:119], 0, v[144:145]
	global_load_dwordx4 v[118:121], v[126:127], off offset:16
	global_load_dwordx4 v[122:125], v[126:127], off
	v_lshl_add_u64 v[116:117], v[116:117], 0, v[144:145]
	s_waitcnt vmcnt(1)
	v_pk_add_f32 v[108:109], v[108:109], v[120:121]
	s_waitcnt vmcnt(0)
	v_pk_add_f32 v[112:113], v[112:113], v[124:125]
	v_pk_add_f32 v[110:111], v[110:111], v[122:123]
	v_pk_add_f32 v[106:107], v[106:107], v[118:119]
	global_store_dwordx4 v[116:117], v[110:113], off
	global_store_dwordx4 v[116:117], v[106:109], off offset:16
	v_cvt_pk_bf16_f32 v118, v110, v111
	v_mul_f32_e32 v111, v111, v111
	v_fmac_f32_e32 v111, v110, v110
	v_mul_f32_e32 v110, v113, v113
	v_cvt_pk_bf16_f32 v120, v106, v107
	v_lshlrev_b64 v[122:123], 11, v[114:115]
	v_fmac_f32_e32 v110, v112, v112
	v_mul_f32_e32 v107, v107, v107
	v_lshl_add_u64 v[122:123], s[16:17], 0, v[122:123]
	v_add_f32_e32 v110, v111, v110
	v_fmac_f32_e32 v107, v106, v106
	v_cvt_pk_bf16_f32 v119, v112, v113
	v_cvt_pk_bf16_f32 v121, v108, v109
	v_lshl_add_u64 v[122:123], v[140:141], 1, v[122:123]
	v_add_f32_e32 v106, v110, v107
	v_mul_f32_e32 v107, v109, v109
	global_store_dwordx4 v[122:123], v[118:121], off sc1
	v_fmac_f32_e32 v107, v108, v108
	s_nop 0
	v_add_f32_e32 v118, v107, v106
	global_load_dwordx4 v[106:109], v[126:127], off offset:528
	global_load_dwordx4 v[110:113], v[126:127], off offset:512
	s_waitcnt vmcnt(1)
	v_pk_add_f32 v[100:101], v[100:101], v[108:109]
	s_waitcnt vmcnt(0)
	v_pk_add_f32 v[104:105], v[104:105], v[112:113]
	v_pk_add_f32 v[102:103], v[102:103], v[110:111]
	v_pk_add_f32 v[98:99], v[98:99], v[106:107]
	global_store_dwordx4 v[116:117], v[102:105], off offset:512
	global_store_dwordx4 v[116:117], v[98:101], off offset:528
	v_cvt_pk_bf16_f32 v106, v102, v103
	v_mul_f32_e32 v103, v103, v103
	v_fmac_f32_e32 v103, v102, v102
	v_mul_f32_e32 v102, v105, v105
	v_cvt_pk_bf16_f32 v108, v98, v99
	v_fmac_f32_e32 v102, v104, v104
	v_mul_f32_e32 v99, v99, v99
	v_add_f32_e32 v102, v103, v102
	v_fmac_f32_e32 v99, v98, v98
	v_add_f32_e32 v98, v102, v99
	v_mul_f32_e32 v99, v101, v101
	v_fmac_f32_e32 v99, v100, v100
	v_add_f32_e32 v98, v99, v98
	v_add_f32_e32 v98, v118, v98
	ds_swizzle_b32 v99, v98 offset:swizzle(SWAP,16)
	v_cvt_pk_bf16_f32 v107, v104, v105
	v_cvt_pk_bf16_f32 v109, v100, v101
	global_store_dwordx4 v[122:123], v[106:109], off offset:256 sc1
	s_waitcnt lgkmcnt(0)
	v_add_f32_e32 v98, v98, v99
	v_mov_b32_e32 v99, v98
	s_nop 1
	v_permlane32_swap_b32_e32 v98, v99
	s_and_saveexec_b64 s[34:35], s[4:5]
	s_cbranch_execz .LBB0_795
	v_lshlrev_b64 v[100:101], 6, v[114:115]
	v_lshl_add_u64 v[100:101], s[14:15], 0, v[100:101]
	v_lshl_add_u64 v[100:101], s[8:9], 2, v[100:101]
	s_lshl_b32 s76, s65, 2
	v_lshl_add_u64 v[100:101], v[100:101], 0, s[76:77]
	v_add_f32_e32 v98, v98, v99
	global_store_dword v[100:101], v98, off
.LBB0_795:
	s_or_b64 exec, exec, s[34:35]
	v_or_b32_e32 v98, 32, v142
	v_ashrrev_i32_e32 v99, 31, v98
	v_lshlrev_b64 v[102:103], 12, v[98:99]
	v_lshl_add_u64 v[100:101], s[12:13], 0, v[102:103]
	v_lshl_add_u64 v[102:103], s[0:1], 0, v[102:103]
	v_lshl_add_u64 v[110:111], v[102:103], 0, v[144:145]
	global_load_dwordx4 v[102:105], v[110:111], off offset:16
	global_load_dwordx4 v[106:109], v[110:111], off
	v_lshl_add_u64 v[100:101], v[100:101], 0, v[144:145]
	s_waitcnt vmcnt(1)
	v_pk_add_f32 v[92:93], v[92:93], v[104:105]
	s_waitcnt vmcnt(0)
	v_pk_add_f32 v[96:97], v[96:97], v[108:109]
	v_pk_add_f32 v[94:95], v[94:95], v[106:107]
	v_pk_add_f32 v[90:91], v[90:91], v[102:103]
	global_store_dwordx4 v[100:101], v[94:97], off
	global_store_dwordx4 v[100:101], v[90:93], off offset:16
	v_cvt_pk_bf16_f32 v102, v94, v95
	v_mul_f32_e32 v95, v95, v95
	v_fmac_f32_e32 v95, v94, v94
	v_mul_f32_e32 v94, v97, v97
	v_cvt_pk_bf16_f32 v104, v90, v91
	v_lshlrev_b64 v[106:107], 11, v[98:99]
	v_fmac_f32_e32 v94, v96, v96
	v_mul_f32_e32 v91, v91, v91
	v_lshl_add_u64 v[106:107], s[16:17], 0, v[106:107]
	v_add_f32_e32 v94, v95, v94
	v_fmac_f32_e32 v91, v90, v90
	v_cvt_pk_bf16_f32 v103, v96, v97
	v_cvt_pk_bf16_f32 v105, v92, v93
	v_lshl_add_u64 v[106:107], v[140:141], 1, v[106:107]
	v_add_f32_e32 v90, v94, v91
	v_mul_f32_e32 v91, v93, v93
	global_store_dwordx4 v[106:107], v[102:105], off sc1
	v_fmac_f32_e32 v91, v92, v92
	s_nop 0
	v_add_f32_e32 v102, v91, v90
	global_load_dwordx4 v[90:93], v[110:111], off offset:528
	global_load_dwordx4 v[94:97], v[110:111], off offset:512
	s_waitcnt vmcnt(1)
	v_pk_add_f32 v[84:85], v[84:85], v[92:93]
	s_waitcnt vmcnt(0)
	v_pk_add_f32 v[88:89], v[88:89], v[96:97]
	v_pk_add_f32 v[86:87], v[86:87], v[94:95]
	v_pk_add_f32 v[82:83], v[82:83], v[90:91]
	global_store_dwordx4 v[100:101], v[86:89], off offset:512
	global_store_dwordx4 v[100:101], v[82:85], off offset:528
	v_cvt_pk_bf16_f32 v90, v86, v87
	v_mul_f32_e32 v87, v87, v87
	v_fmac_f32_e32 v87, v86, v86
	v_mul_f32_e32 v86, v89, v89
	v_cvt_pk_bf16_f32 v92, v82, v83
	v_fmac_f32_e32 v86, v88, v88
	v_mul_f32_e32 v83, v83, v83
	v_add_f32_e32 v86, v87, v86
	v_fmac_f32_e32 v83, v82, v82
	v_add_f32_e32 v82, v86, v83
	v_mul_f32_e32 v83, v85, v85
	v_fmac_f32_e32 v83, v84, v84
	v_add_f32_e32 v82, v83, v82
	v_add_f32_e32 v82, v102, v82
	ds_swizzle_b32 v83, v82 offset:swizzle(SWAP,16)
	v_cvt_pk_bf16_f32 v91, v88, v89
	v_cvt_pk_bf16_f32 v93, v84, v85
	global_store_dwordx4 v[106:107], v[90:93], off offset:256 sc1
	s_waitcnt lgkmcnt(0)
	v_add_f32_e32 v82, v82, v83
	v_mov_b32_e32 v83, v82
	s_nop 1
	v_permlane32_swap_b32_e32 v82, v83
	s_and_saveexec_b64 s[34:35], s[4:5]
	s_cbranch_execz .LBB0_797
	v_lshlrev_b64 v[84:85], 6, v[98:99]
	v_lshl_add_u64 v[84:85], s[14:15], 0, v[84:85]
	v_lshl_add_u64 v[84:85], s[8:9], 2, v[84:85]
	s_lshl_b32 s76, s65, 2
	v_lshl_add_u64 v[84:85], v[84:85], 0, s[76:77]
	v_add_f32_e32 v82, v82, v83
	global_store_dword v[84:85], v82, off
.LBB0_797:
	s_or_b64 exec, exec, s[34:35]
	v_or_b32_e32 v82, 48, v142
	v_ashrrev_i32_e32 v83, 31, v82
	v_lshlrev_b64 v[86:87], 12, v[82:83]
	v_lshl_add_u64 v[84:85], s[12:13], 0, v[86:87]
	v_lshl_add_u64 v[86:87], s[0:1], 0, v[86:87]
	v_lshl_add_u64 v[94:95], v[86:87], 0, v[144:145]
	global_load_dwordx4 v[86:89], v[94:95], off offset:16
	global_load_dwordx4 v[90:93], v[94:95], off
	v_lshl_add_u64 v[84:85], v[84:85], 0, v[144:145]
	s_waitcnt vmcnt(1)
	v_pk_add_f32 v[76:77], v[76:77], v[88:89]
	s_waitcnt vmcnt(0)
	v_pk_add_f32 v[80:81], v[80:81], v[92:93]
	v_pk_add_f32 v[78:79], v[78:79], v[90:91]
	v_pk_add_f32 v[74:75], v[74:75], v[86:87]
	global_store_dwordx4 v[84:85], v[78:81], off
	global_store_dwordx4 v[84:85], v[74:77], off offset:16
	v_cvt_pk_bf16_f32 v86, v78, v79
	v_mul_f32_e32 v79, v79, v79
	v_fmac_f32_e32 v79, v78, v78
	v_mul_f32_e32 v78, v81, v81
	v_cvt_pk_bf16_f32 v88, v74, v75
	v_lshlrev_b64 v[90:91], 11, v[82:83]
	v_fmac_f32_e32 v78, v80, v80
	v_mul_f32_e32 v75, v75, v75
	v_lshl_add_u64 v[90:91], s[16:17], 0, v[90:91]
	v_add_f32_e32 v78, v79, v78
	v_fmac_f32_e32 v75, v74, v74
	v_cvt_pk_bf16_f32 v87, v80, v81
	v_cvt_pk_bf16_f32 v89, v76, v77
	v_lshl_add_u64 v[90:91], v[140:141], 1, v[90:91]
	v_add_f32_e32 v74, v78, v75
	v_mul_f32_e32 v75, v77, v77
	global_store_dwordx4 v[90:91], v[86:89], off sc1
	v_fmac_f32_e32 v75, v76, v76
	s_nop 0
	v_add_f32_e32 v86, v75, v74
	global_load_dwordx4 v[74:77], v[94:95], off offset:528
	global_load_dwordx4 v[78:81], v[94:95], off offset:512
	s_waitcnt vmcnt(1)
	v_pk_add_f32 v[68:69], v[68:69], v[76:77]
	s_waitcnt vmcnt(0)
	v_pk_add_f32 v[72:73], v[72:73], v[80:81]
	v_pk_add_f32 v[70:71], v[70:71], v[78:79]
	v_pk_add_f32 v[66:67], v[66:67], v[74:75]
	global_store_dwordx4 v[84:85], v[70:73], off offset:512
	global_store_dwordx4 v[84:85], v[66:69], off offset:528
	v_cvt_pk_bf16_f32 v74, v70, v71
	v_mul_f32_e32 v71, v71, v71
	v_fmac_f32_e32 v71, v70, v70
	v_mul_f32_e32 v70, v73, v73
	v_cvt_pk_bf16_f32 v76, v66, v67
	v_fmac_f32_e32 v70, v72, v72
	v_mul_f32_e32 v67, v67, v67
	v_add_f32_e32 v70, v71, v70
	v_fmac_f32_e32 v67, v66, v66
	v_add_f32_e32 v66, v70, v67
	v_mul_f32_e32 v67, v69, v69
	v_fmac_f32_e32 v67, v68, v68
	v_add_f32_e32 v66, v67, v66
	v_add_f32_e32 v66, v86, v66
	ds_swizzle_b32 v67, v66 offset:swizzle(SWAP,16)
	v_cvt_pk_bf16_f32 v75, v72, v73
	v_cvt_pk_bf16_f32 v77, v68, v69
	global_store_dwordx4 v[90:91], v[74:77], off offset:256 sc1
	s_waitcnt lgkmcnt(0)
	v_add_f32_e32 v66, v66, v67
	v_mov_b32_e32 v67, v66
	s_nop 1
	v_permlane32_swap_b32_e32 v66, v67
	s_and_saveexec_b64 s[34:35], s[4:5]
	s_cbranch_execz .LBB0_799
	v_lshlrev_b64 v[68:69], 6, v[82:83]
	v_lshl_add_u64 v[68:69], s[14:15], 0, v[68:69]
	v_lshl_add_u64 v[68:69], s[8:9], 2, v[68:69]
	s_lshl_b32 s76, s65, 2
	v_lshl_add_u64 v[68:69], v[68:69], 0, s[76:77]
	v_add_f32_e32 v66, v66, v67
	global_store_dword v[68:69], v66, off
.LBB0_799:
	s_or_b64 exec, exec, s[34:35]
	v_add_u32_e32 v66, 0x80, v142
	v_ashrrev_i32_e32 v67, 31, v66
	v_lshlrev_b64 v[70:71], 12, v[66:67]
	v_lshl_add_u64 v[68:69], s[12:13], 0, v[70:71]
	v_lshl_add_u64 v[70:71], s[0:1], 0, v[70:71]
	v_lshl_add_u64 v[78:79], v[70:71], 0, v[144:145]
	global_load_dwordx4 v[70:73], v[78:79], off offset:16
	global_load_dwordx4 v[74:77], v[78:79], off
	v_lshl_add_u64 v[68:69], v[68:69], 0, v[144:145]
	s_waitcnt vmcnt(1)
	v_pk_add_f32 v[60:61], v[60:61], v[72:73]
	s_waitcnt vmcnt(0)
	v_pk_add_f32 v[64:65], v[64:65], v[76:77]
	v_pk_add_f32 v[62:63], v[62:63], v[74:75]
	v_pk_add_f32 v[58:59], v[58:59], v[70:71]
	global_store_dwordx4 v[68:69], v[62:65], off
	global_store_dwordx4 v[68:69], v[58:61], off offset:16
	v_cvt_pk_bf16_f32 v70, v62, v63
	v_mul_f32_e32 v63, v63, v63
	v_fmac_f32_e32 v63, v62, v62
	v_mul_f32_e32 v62, v65, v65
	v_cvt_pk_bf16_f32 v72, v58, v59
	v_lshlrev_b64 v[74:75], 11, v[66:67]
	v_fmac_f32_e32 v62, v64, v64
	v_mul_f32_e32 v59, v59, v59
	v_lshl_add_u64 v[74:75], s[16:17], 0, v[74:75]
	v_add_f32_e32 v62, v63, v62
	v_fmac_f32_e32 v59, v58, v58
	v_cvt_pk_bf16_f32 v71, v64, v65
	v_cvt_pk_bf16_f32 v73, v60, v61
	v_lshl_add_u64 v[74:75], v[140:141], 1, v[74:75]
	v_add_f32_e32 v58, v62, v59
	v_mul_f32_e32 v59, v61, v61
	global_store_dwordx4 v[74:75], v[70:73], off sc1
	v_fmac_f32_e32 v59, v60, v60
	s_nop 0
	v_add_f32_e32 v70, v59, v58
	global_load_dwordx4 v[58:61], v[78:79], off offset:528
	global_load_dwordx4 v[62:65], v[78:79], off offset:512
	s_waitcnt vmcnt(1)
	v_pk_add_f32 v[52:53], v[52:53], v[60:61]
	s_waitcnt vmcnt(0)
	v_pk_add_f32 v[56:57], v[56:57], v[64:65]
	v_pk_add_f32 v[54:55], v[54:55], v[62:63]
	v_pk_add_f32 v[50:51], v[50:51], v[58:59]
	global_store_dwordx4 v[68:69], v[54:57], off offset:512
	global_store_dwordx4 v[68:69], v[50:53], off offset:528
	v_cvt_pk_bf16_f32 v58, v54, v55
	v_mul_f32_e32 v55, v55, v55
	v_fmac_f32_e32 v55, v54, v54
	v_mul_f32_e32 v54, v57, v57
	v_cvt_pk_bf16_f32 v60, v50, v51
	v_fmac_f32_e32 v54, v56, v56
	v_mul_f32_e32 v51, v51, v51
	v_add_f32_e32 v54, v55, v54
	v_fmac_f32_e32 v51, v50, v50
	v_add_f32_e32 v50, v54, v51
	v_mul_f32_e32 v51, v53, v53
	v_fmac_f32_e32 v51, v52, v52
	v_add_f32_e32 v50, v51, v50
	v_add_f32_e32 v50, v70, v50
	ds_swizzle_b32 v51, v50 offset:swizzle(SWAP,16)
	v_cvt_pk_bf16_f32 v59, v56, v57
	v_cvt_pk_bf16_f32 v61, v52, v53
	global_store_dwordx4 v[74:75], v[58:61], off offset:256 sc1
	s_waitcnt lgkmcnt(0)
	v_add_f32_e32 v50, v50, v51
	v_mov_b32_e32 v51, v50
	s_nop 1
	v_permlane32_swap_b32_e32 v50, v51
	s_and_saveexec_b64 s[34:35], s[4:5]
	s_cbranch_execz .LBB0_801
	v_lshlrev_b64 v[52:53], 6, v[66:67]
	v_lshl_add_u64 v[52:53], s[14:15], 0, v[52:53]
	v_lshl_add_u64 v[52:53], s[8:9], 2, v[52:53]
	s_lshl_b32 s76, s65, 2
	v_lshl_add_u64 v[52:53], v[52:53], 0, s[76:77]
	v_add_f32_e32 v50, v50, v51
	global_store_dword v[52:53], v50, off
.LBB0_801:
	s_or_b64 exec, exec, s[34:35]
	v_add_u32_e32 v50, 0x90, v142
	v_ashrrev_i32_e32 v51, 31, v50
	v_lshlrev_b64 v[54:55], 12, v[50:51]
	v_lshl_add_u64 v[52:53], s[12:13], 0, v[54:55]
	v_lshl_add_u64 v[54:55], s[0:1], 0, v[54:55]
	v_lshl_add_u64 v[62:63], v[54:55], 0, v[144:145]
	global_load_dwordx4 v[54:57], v[62:63], off offset:16
	global_load_dwordx4 v[58:61], v[62:63], off
	v_lshl_add_u64 v[52:53], v[52:53], 0, v[144:145]
	s_waitcnt vmcnt(1)
	v_pk_add_f32 v[44:45], v[44:45], v[56:57]
	s_waitcnt vmcnt(0)
	v_pk_add_f32 v[48:49], v[48:49], v[60:61]
	v_pk_add_f32 v[46:47], v[46:47], v[58:59]
	v_pk_add_f32 v[42:43], v[42:43], v[54:55]
	global_store_dwordx4 v[52:53], v[46:49], off
	global_store_dwordx4 v[52:53], v[42:45], off offset:16
	v_cvt_pk_bf16_f32 v54, v46, v47
	v_mul_f32_e32 v47, v47, v47
	v_fmac_f32_e32 v47, v46, v46
	v_mul_f32_e32 v46, v49, v49
	v_cvt_pk_bf16_f32 v56, v42, v43
	v_lshlrev_b64 v[58:59], 11, v[50:51]
	v_fmac_f32_e32 v46, v48, v48
	v_mul_f32_e32 v43, v43, v43
	v_lshl_add_u64 v[58:59], s[16:17], 0, v[58:59]
	v_add_f32_e32 v46, v47, v46
	v_fmac_f32_e32 v43, v42, v42
	v_cvt_pk_bf16_f32 v55, v48, v49
	v_cvt_pk_bf16_f32 v57, v44, v45
	v_lshl_add_u64 v[58:59], v[140:141], 1, v[58:59]
	v_add_f32_e32 v42, v46, v43
	v_mul_f32_e32 v43, v45, v45
	global_store_dwordx4 v[58:59], v[54:57], off sc1
	v_fmac_f32_e32 v43, v44, v44
	s_nop 0
	v_add_f32_e32 v54, v43, v42
	global_load_dwordx4 v[42:45], v[62:63], off offset:528
	global_load_dwordx4 v[46:49], v[62:63], off offset:512
	s_waitcnt vmcnt(1)
	v_pk_add_f32 v[36:37], v[36:37], v[44:45]
	s_waitcnt vmcnt(0)
	v_pk_add_f32 v[40:41], v[40:41], v[48:49]
	v_pk_add_f32 v[38:39], v[38:39], v[46:47]
	v_pk_add_f32 v[34:35], v[34:35], v[42:43]
	global_store_dwordx4 v[52:53], v[38:41], off offset:512
	global_store_dwordx4 v[52:53], v[34:37], off offset:528
	v_cvt_pk_bf16_f32 v42, v38, v39
	v_mul_f32_e32 v39, v39, v39
	v_fmac_f32_e32 v39, v38, v38
	v_mul_f32_e32 v38, v41, v41
	v_cvt_pk_bf16_f32 v44, v34, v35
	v_fmac_f32_e32 v38, v40, v40
	v_mul_f32_e32 v35, v35, v35
	v_add_f32_e32 v38, v39, v38
	v_fmac_f32_e32 v35, v34, v34
	v_add_f32_e32 v34, v38, v35
	v_mul_f32_e32 v35, v37, v37
	v_fmac_f32_e32 v35, v36, v36
	v_add_f32_e32 v34, v35, v34
	v_add_f32_e32 v34, v54, v34
	ds_swizzle_b32 v35, v34 offset:swizzle(SWAP,16)
	v_cvt_pk_bf16_f32 v43, v40, v41
	v_cvt_pk_bf16_f32 v45, v36, v37
	global_store_dwordx4 v[58:59], v[42:45], off offset:256 sc1
	s_waitcnt lgkmcnt(0)
	v_add_f32_e32 v34, v34, v35
	v_mov_b32_e32 v35, v34
	s_nop 1
	v_permlane32_swap_b32_e32 v34, v35
	s_and_saveexec_b64 s[34:35], s[4:5]
	s_cbranch_execz .LBB0_803
	v_lshlrev_b64 v[36:37], 6, v[50:51]
	v_lshl_add_u64 v[36:37], s[14:15], 0, v[36:37]
	v_lshl_add_u64 v[36:37], s[8:9], 2, v[36:37]
	s_lshl_b32 s76, s65, 2
	v_lshl_add_u64 v[36:37], v[36:37], 0, s[76:77]
	v_add_f32_e32 v34, v34, v35
	global_store_dword v[36:37], v34, off
.LBB0_803:
	s_or_b64 exec, exec, s[34:35]
	v_add_u32_e32 v34, 0xa0, v142
	v_ashrrev_i32_e32 v35, 31, v34
	v_lshlrev_b64 v[38:39], 12, v[34:35]
	v_lshl_add_u64 v[36:37], s[12:13], 0, v[38:39]
	v_lshl_add_u64 v[38:39], s[0:1], 0, v[38:39]
	v_lshl_add_u64 v[46:47], v[38:39], 0, v[144:145]
	global_load_dwordx4 v[38:41], v[46:47], off offset:16
	global_load_dwordx4 v[42:45], v[46:47], off
	v_lshl_add_u64 v[36:37], v[36:37], 0, v[144:145]
	s_waitcnt vmcnt(1)
	v_pk_add_f32 v[28:29], v[28:29], v[40:41]
	s_waitcnt vmcnt(0)
	v_pk_add_f32 v[32:33], v[32:33], v[44:45]
	v_pk_add_f32 v[30:31], v[30:31], v[42:43]
	v_pk_add_f32 v[26:27], v[26:27], v[38:39]
	global_store_dwordx4 v[36:37], v[30:33], off
	global_store_dwordx4 v[36:37], v[26:29], off offset:16
	v_cvt_pk_bf16_f32 v38, v30, v31
	v_mul_f32_e32 v31, v31, v31
	v_fmac_f32_e32 v31, v30, v30
	v_mul_f32_e32 v30, v33, v33
	v_cvt_pk_bf16_f32 v40, v26, v27
	v_lshlrev_b64 v[42:43], 11, v[34:35]
	v_fmac_f32_e32 v30, v32, v32
	v_mul_f32_e32 v27, v27, v27
	v_lshl_add_u64 v[42:43], s[16:17], 0, v[42:43]
	v_add_f32_e32 v30, v31, v30
	v_fmac_f32_e32 v27, v26, v26
	v_cvt_pk_bf16_f32 v39, v32, v33
	v_cvt_pk_bf16_f32 v41, v28, v29
	v_lshl_add_u64 v[42:43], v[140:141], 1, v[42:43]
	v_add_f32_e32 v26, v30, v27
	v_mul_f32_e32 v27, v29, v29
	global_store_dwordx4 v[42:43], v[38:41], off sc1
	v_fmac_f32_e32 v27, v28, v28
	s_nop 0
	v_add_f32_e32 v38, v27, v26
	global_load_dwordx4 v[26:29], v[46:47], off offset:528
	global_load_dwordx4 v[30:33], v[46:47], off offset:512
	s_waitcnt vmcnt(1)
	v_pk_add_f32 v[20:21], v[20:21], v[28:29]
	s_waitcnt vmcnt(0)
	v_pk_add_f32 v[24:25], v[24:25], v[32:33]
	v_pk_add_f32 v[22:23], v[22:23], v[30:31]
	v_pk_add_f32 v[18:19], v[18:19], v[26:27]
	global_store_dwordx4 v[36:37], v[22:25], off offset:512
	global_store_dwordx4 v[36:37], v[18:21], off offset:528
	v_cvt_pk_bf16_f32 v26, v22, v23
	v_mul_f32_e32 v23, v23, v23
	v_fmac_f32_e32 v23, v22, v22
	v_mul_f32_e32 v22, v25, v25
	v_cvt_pk_bf16_f32 v28, v18, v19
	v_fmac_f32_e32 v22, v24, v24
	v_mul_f32_e32 v19, v19, v19
	v_add_f32_e32 v22, v23, v22
	v_fmac_f32_e32 v19, v18, v18
	v_add_f32_e32 v18, v22, v19
	v_mul_f32_e32 v19, v21, v21
	v_fmac_f32_e32 v19, v20, v20
	v_add_f32_e32 v18, v19, v18
	v_add_f32_e32 v18, v38, v18
	ds_swizzle_b32 v19, v18 offset:swizzle(SWAP,16)
	v_cvt_pk_bf16_f32 v27, v24, v25
	v_cvt_pk_bf16_f32 v29, v20, v21
	global_store_dwordx4 v[42:43], v[26:29], off offset:256 sc1
	s_waitcnt lgkmcnt(0)
	v_add_f32_e32 v18, v18, v19
	v_mov_b32_e32 v19, v18
	s_nop 1
	v_permlane32_swap_b32_e32 v18, v19
	s_and_saveexec_b64 s[34:35], s[4:5]
	s_cbranch_execz .LBB0_805
	v_lshlrev_b64 v[20:21], 6, v[34:35]
	v_lshl_add_u64 v[20:21], s[14:15], 0, v[20:21]
	v_lshl_add_u64 v[20:21], s[8:9], 2, v[20:21]
	s_lshl_b32 s76, s65, 2
	v_lshl_add_u64 v[20:21], v[20:21], 0, s[76:77]
	v_add_f32_e32 v18, v18, v19
	global_store_dword v[20:21], v18, off
.LBB0_805:
	s_or_b64 exec, exec, s[34:35]
	v_add_u32_e32 v18, 0xb0, v142
	v_ashrrev_i32_e32 v19, 31, v18
	v_lshlrev_b64 v[22:23], 12, v[18:19]
	v_lshl_add_u64 v[20:21], s[12:13], 0, v[22:23]
	v_lshl_add_u64 v[22:23], s[0:1], 0, v[22:23]
	v_lshl_add_u64 v[30:31], v[22:23], 0, v[144:145]
	global_load_dwordx4 v[22:25], v[30:31], off offset:16
	global_load_dwordx4 v[26:29], v[30:31], off
	v_lshl_add_u64 v[20:21], v[20:21], 0, v[144:145]
	s_waitcnt vmcnt(1)
	v_pk_add_f32 v[12:13], v[12:13], v[24:25]
	s_waitcnt vmcnt(0)
	v_pk_add_f32 v[16:17], v[16:17], v[28:29]
	v_pk_add_f32 v[14:15], v[14:15], v[26:27]
	v_pk_add_f32 v[10:11], v[10:11], v[22:23]
	global_store_dwordx4 v[20:21], v[14:17], off
	global_store_dwordx4 v[20:21], v[10:13], off offset:16
	v_cvt_pk_bf16_f32 v22, v14, v15
	v_mul_f32_e32 v15, v15, v15
	v_fmac_f32_e32 v15, v14, v14
	v_mul_f32_e32 v14, v17, v17
	v_cvt_pk_bf16_f32 v24, v10, v11
	v_lshlrev_b64 v[26:27], 11, v[18:19]
	v_fmac_f32_e32 v14, v16, v16
	v_mul_f32_e32 v11, v11, v11
	v_lshl_add_u64 v[26:27], s[16:17], 0, v[26:27]
	v_add_f32_e32 v14, v15, v14
	v_fmac_f32_e32 v11, v10, v10
	v_cvt_pk_bf16_f32 v23, v16, v17
	v_cvt_pk_bf16_f32 v25, v12, v13
	v_lshl_add_u64 v[26:27], v[140:141], 1, v[26:27]
	v_add_f32_e32 v10, v14, v11
	v_mul_f32_e32 v11, v13, v13
	global_store_dwordx4 v[26:27], v[22:25], off sc1
	v_fmac_f32_e32 v11, v12, v12
	s_nop 0
	v_add_f32_e32 v22, v11, v10
	global_load_dwordx4 v[10:13], v[30:31], off offset:528
	global_load_dwordx4 v[14:17], v[30:31], off offset:512
	s_waitcnt vmcnt(1)
	v_pk_add_f32 v[4:5], v[4:5], v[12:13]
	s_waitcnt vmcnt(0)
	v_pk_add_f32 v[8:9], v[8:9], v[16:17]
	v_pk_add_f32 v[6:7], v[6:7], v[14:15]
	v_pk_add_f32 v[2:3], v[2:3], v[10:11]
	global_store_dwordx4 v[20:21], v[6:9], off offset:512
	global_store_dwordx4 v[20:21], v[2:5], off offset:528
	v_cvt_pk_bf16_f32 v10, v6, v7
	v_mul_f32_e32 v7, v7, v7
	v_fmac_f32_e32 v7, v6, v6
	v_mul_f32_e32 v6, v9, v9
	v_cvt_pk_bf16_f32 v12, v2, v3
	v_fmac_f32_e32 v6, v8, v8
	v_mul_f32_e32 v3, v3, v3
	v_add_f32_e32 v6, v7, v6
	v_fmac_f32_e32 v3, v2, v2
	v_add_f32_e32 v2, v6, v3
	v_mul_f32_e32 v3, v5, v5
	v_fmac_f32_e32 v3, v4, v4
	v_add_f32_e32 v2, v3, v2
	v_add_f32_e32 v2, v22, v2
	ds_swizzle_b32 v3, v2 offset:swizzle(SWAP,16)
	v_cvt_pk_bf16_f32 v11, v8, v9
	v_cvt_pk_bf16_f32 v13, v4, v5
	global_store_dwordx4 v[26:27], v[10:13], off offset:256 sc1
	s_waitcnt lgkmcnt(0)
	v_add_f32_e32 v2, v2, v3
	v_mov_b32_e32 v3, v2
	s_nop 1
	v_permlane32_swap_b32_e32 v2, v3
	s_and_saveexec_b64 s[34:35], s[4:5]
	s_cbranch_execz .LBB0_780
	v_lshlrev_b64 v[4:5], 6, v[18:19]
	v_lshl_add_u64 v[4:5], s[14:15], 0, v[4:5]
	v_lshl_add_u64 v[4:5], s[8:9], 2, v[4:5]
	s_lshl_b32 s76, s65, 2
	v_lshl_add_u64 v[4:5], v[4:5], 0, s[76:77]
	v_add_f32_e32 v2, v2, v3
	global_store_dword v[4:5], v2, off
	s_branch .LBB0_780

.LBB0_953:
	s_mov_b32 s8, s77
	s_lshl_b32 s8, s59, 2
	v_lshl_add_u32 v142, s58, 8, v146
	v_ashrrev_i32_e32 v143, 31, v142
	v_lshl_or_b32 v140, s59, 8, v148
	v_lshlrev_b64 v[144:145], 12, v[142:143]
	v_lshl_add_u64 v[144:145], s[12:13], 0, v[144:145]
	v_ashrrev_i32_e32 v141, 31, v140
	v_lshl_add_u64 v[144:145], v[140:141], 2, v[144:145]
	global_load_dwordx4 v[150:153], v[144:145], off offset:16
	global_load_dwordx4 v[154:157], v[144:145], off
	s_ashr_i32 s9, s8, 31
	s_waitcnt vmcnt(0)
	v_pk_add_f32 v[124:125], v[124:125], v[152:153]
	v_pk_add_f32 v[128:129], v[128:129], v[156:157]
	v_pk_add_f32 v[126:127], v[126:127], v[154:155]
	v_pk_add_f32 v[122:123], v[122:123], v[150:151]
	global_store_dwordx4 v[144:145], v[126:129], off
	global_store_dwordx4 v[144:145], v[122:125], off offset:16
	v_cvt_pk_bf16_f32 v150, v126, v127
	v_mul_f32_e32 v127, v127, v127
	v_fmac_f32_e32 v127, v126, v126
	v_mul_f32_e32 v126, v129, v129
	v_cvt_pk_bf16_f32 v152, v122, v123
	v_lshlrev_b64 v[154:155], 11, v[142:143]
	v_fmac_f32_e32 v126, v128, v128
	v_mul_f32_e32 v123, v123, v123
	v_lshl_add_u64 v[154:155], s[18:19], 0, v[154:155]
	v_add_f32_e32 v126, v127, v126
	v_fmac_f32_e32 v123, v122, v122
	v_cvt_pk_bf16_f32 v151, v128, v129
	v_cvt_pk_bf16_f32 v153, v124, v125
	v_lshl_add_u64 v[154:155], v[140:141], 1, v[154:155]
	v_add_f32_e32 v122, v126, v123
	v_mul_f32_e32 v123, v125, v125
	global_store_dwordx4 v[154:155], v[150:153], off sc1
	v_fmac_f32_e32 v123, v124, v124
	s_nop 0
	v_add_f32_e32 v150, v123, v122
	global_load_dwordx4 v[122:125], v[144:145], off offset:528
	global_load_dwordx4 v[126:129], v[144:145], off offset:512
	s_waitcnt vmcnt(0)
	v_pk_add_f32 v[116:117], v[116:117], v[124:125]
	v_pk_add_f32 v[120:121], v[120:121], v[128:129]
	v_pk_add_f32 v[118:119], v[118:119], v[126:127]
	v_pk_add_f32 v[114:115], v[114:115], v[122:123]
	global_store_dwordx4 v[144:145], v[118:121], off offset:512
	global_store_dwordx4 v[144:145], v[114:117], off offset:528
	v_cvt_pk_bf16_f32 v122, v118, v119
	v_mul_f32_e32 v119, v119, v119
	v_fmac_f32_e32 v119, v118, v118
	v_mul_f32_e32 v118, v121, v121
	v_cvt_pk_bf16_f32 v124, v114, v115
	v_fmac_f32_e32 v118, v120, v120
	v_mul_f32_e32 v115, v115, v115
	v_add_f32_e32 v118, v119, v118
	v_fmac_f32_e32 v115, v114, v114
	v_add_f32_e32 v114, v118, v115
	v_mul_f32_e32 v115, v117, v117
	v_fmac_f32_e32 v115, v116, v116
	v_add_f32_e32 v114, v115, v114
	v_add_f32_e32 v114, v150, v114
	ds_swizzle_b32 v115, v114 offset:swizzle(SWAP,16)
	v_cvt_pk_bf16_f32 v123, v120, v121
	v_cvt_pk_bf16_f32 v125, v116, v117
	global_store_dwordx4 v[154:155], v[122:125], off offset:256 sc1
	s_waitcnt lgkmcnt(0)
	v_add_f32_e32 v114, v114, v115
	v_mov_b32_e32 v115, v114
	s_nop 1
	v_permlane32_swap_b32_e32 v114, v115
	s_and_saveexec_b64 s[34:35], s[4:5]
	s_cbranch_execz .LBB0_955
	v_lshlrev_b64 v[116:117], 6, v[142:143]
	v_lshl_add_u64 v[116:117], s[40:41], 0, v[116:117]
	v_lshl_add_u64 v[116:117], s[8:9], 2, v[116:117]
	s_lshl_b32 s76, s44, 2
	v_lshl_add_u64 v[116:117], v[116:117], 0, s[76:77]
	v_add_f32_e32 v114, v114, v115
	global_store_dword v[116:117], v114, off
.LBB0_955:
	s_or_b64 exec, exec, s[34:35]
	v_or_b32_e32 v114, 16, v142
	v_ashrrev_i32_e32 v115, 31, v114
	v_lshlrev_b64 v[116:117], 12, v[114:115]
	v_lshl_add_u64 v[116:117], s[12:13], 0, v[116:117]
	v_lshl_add_u64 v[116:117], v[140:141], 2, v[116:117]
	global_load_dwordx4 v[118:121], v[116:117], off offset:16
	global_load_dwordx4 v[122:125], v[116:117], off
	s_waitcnt vmcnt(1)
	v_pk_add_f32 v[108:109], v[108:109], v[120:121]
	s_waitcnt vmcnt(0)
	v_pk_add_f32 v[112:113], v[112:113], v[124:125]
	v_pk_add_f32 v[110:111], v[110:111], v[122:123]
	v_pk_add_f32 v[106:107], v[106:107], v[118:119]
	global_store_dwordx4 v[116:117], v[110:113], off
	global_store_dwordx4 v[116:117], v[106:109], off offset:16
	v_cvt_pk_bf16_f32 v118, v110, v111
	v_mul_f32_e32 v111, v111, v111
	v_fmac_f32_e32 v111, v110, v110
	v_mul_f32_e32 v110, v113, v113
	v_cvt_pk_bf16_f32 v120, v106, v107
	v_lshlrev_b64 v[122:123], 11, v[114:115]
	v_fmac_f32_e32 v110, v112, v112
	v_mul_f32_e32 v107, v107, v107
	v_lshl_add_u64 v[122:123], s[18:19], 0, v[122:123]
	v_add_f32_e32 v110, v111, v110
	v_fmac_f32_e32 v107, v106, v106
	v_cvt_pk_bf16_f32 v119, v112, v113
	v_cvt_pk_bf16_f32 v121, v108, v109
	v_lshl_add_u64 v[122:123], v[140:141], 1, v[122:123]
	v_add_f32_e32 v106, v110, v107
	v_mul_f32_e32 v107, v109, v109
	global_store_dwordx4 v[122:123], v[118:121], off sc1
	v_fmac_f32_e32 v107, v108, v108
	s_nop 0
	v_add_f32_e32 v118, v107, v106
	global_load_dwordx4 v[106:109], v[116:117], off offset:528
	global_load_dwordx4 v[110:113], v[116:117], off offset:512
	s_waitcnt vmcnt(1)
	v_pk_add_f32 v[100:101], v[100:101], v[108:109]
	s_waitcnt vmcnt(0)
	v_pk_add_f32 v[104:105], v[104:105], v[112:113]
	v_pk_add_f32 v[102:103], v[102:103], v[110:111]
	v_pk_add_f32 v[98:99], v[98:99], v[106:107]
	global_store_dwordx4 v[116:117], v[102:105], off offset:512
	global_store_dwordx4 v[116:117], v[98:101], off offset:528
	v_cvt_pk_bf16_f32 v106, v102, v103
	v_mul_f32_e32 v103, v103, v103
	v_fmac_f32_e32 v103, v102, v102
	v_mul_f32_e32 v102, v105, v105
	v_cvt_pk_bf16_f32 v108, v98, v99
	v_fmac_f32_e32 v102, v104, v104
	v_mul_f32_e32 v99, v99, v99
	v_add_f32_e32 v102, v103, v102
	v_fmac_f32_e32 v99, v98, v98
	v_add_f32_e32 v98, v102, v99
	v_mul_f32_e32 v99, v101, v101
	v_fmac_f32_e32 v99, v100, v100
	v_add_f32_e32 v98, v99, v98
	v_add_f32_e32 v98, v118, v98
	ds_swizzle_b32 v99, v98 offset:swizzle(SWAP,16)
	v_cvt_pk_bf16_f32 v107, v104, v105
	v_cvt_pk_bf16_f32 v109, v100, v101
	global_store_dwordx4 v[122:123], v[106:109], off offset:256 sc1
	s_waitcnt lgkmcnt(0)
	v_add_f32_e32 v98, v98, v99
	v_mov_b32_e32 v99, v98
	s_nop 1
	v_permlane32_swap_b32_e32 v98, v99
	s_and_saveexec_b64 s[34:35], s[4:5]
	s_cbranch_execz .LBB0_957
	v_lshlrev_b64 v[100:101], 6, v[114:115]
	v_lshl_add_u64 v[100:101], s[40:41], 0, v[100:101]
	v_lshl_add_u64 v[100:101], s[8:9], 2, v[100:101]
	s_lshl_b32 s76, s44, 2
	v_lshl_add_u64 v[100:101], v[100:101], 0, s[76:77]
	v_add_f32_e32 v98, v98, v99
	global_store_dword v[100:101], v98, off
.LBB0_957:
	s_or_b64 exec, exec, s[34:35]
	v_or_b32_e32 v98, 32, v142
	v_ashrrev_i32_e32 v99, 31, v98
	v_lshlrev_b64 v[100:101], 12, v[98:99]
	v_lshl_add_u64 v[100:101], s[12:13], 0, v[100:101]
	v_lshl_add_u64 v[100:101], v[140:141], 2, v[100:101]
	global_load_dwordx4 v[102:105], v[100:101], off offset:16
	global_load_dwordx4 v[106:109], v[100:101], off
	s_waitcnt vmcnt(1)
	v_pk_add_f32 v[92:93], v[92:93], v[104:105]
	s_waitcnt vmcnt(0)
	v_pk_add_f32 v[96:97], v[96:97], v[108:109]
	v_pk_add_f32 v[94:95], v[94:95], v[106:107]
	v_pk_add_f32 v[90:91], v[90:91], v[102:103]
	global_store_dwordx4 v[100:101], v[94:97], off
	global_store_dwordx4 v[100:101], v[90:93], off offset:16
	v_cvt_pk_bf16_f32 v102, v94, v95
	v_mul_f32_e32 v95, v95, v95
	v_fmac_f32_e32 v95, v94, v94
	v_mul_f32_e32 v94, v97, v97
	v_cvt_pk_bf16_f32 v104, v90, v91
	v_lshlrev_b64 v[106:107], 11, v[98:99]
	v_fmac_f32_e32 v94, v96, v96
	v_mul_f32_e32 v91, v91, v91
	v_lshl_add_u64 v[106:107], s[18:19], 0, v[106:107]
	v_add_f32_e32 v94, v95, v94
	v_fmac_f32_e32 v91, v90, v90
	v_cvt_pk_bf16_f32 v103, v96, v97
	v_cvt_pk_bf16_f32 v105, v92, v93
	v_lshl_add_u64 v[106:107], v[140:141], 1, v[106:107]
	v_add_f32_e32 v90, v94, v91
	v_mul_f32_e32 v91, v93, v93
	global_store_dwordx4 v[106:107], v[102:105], off sc1
	v_fmac_f32_e32 v91, v92, v92
	s_nop 0
	v_add_f32_e32 v102, v91, v90
	global_load_dwordx4 v[90:93], v[100:101], off offset:528
	global_load_dwordx4 v[94:97], v[100:101], off offset:512
	s_waitcnt vmcnt(1)
	v_pk_add_f32 v[84:85], v[84:85], v[92:93]
	s_waitcnt vmcnt(0)
	v_pk_add_f32 v[88:89], v[88:89], v[96:97]
	v_pk_add_f32 v[86:87], v[86:87], v[94:95]
	v_pk_add_f32 v[82:83], v[82:83], v[90:91]
	global_store_dwordx4 v[100:101], v[86:89], off offset:512
	global_store_dwordx4 v[100:101], v[82:85], off offset:528
	v_cvt_pk_bf16_f32 v90, v86, v87
	v_mul_f32_e32 v87, v87, v87
	v_fmac_f32_e32 v87, v86, v86
	v_mul_f32_e32 v86, v89, v89
	v_cvt_pk_bf16_f32 v92, v82, v83
	v_fmac_f32_e32 v86, v88, v88
	v_mul_f32_e32 v83, v83, v83
	v_add_f32_e32 v86, v87, v86
	v_fmac_f32_e32 v83, v82, v82
	v_add_f32_e32 v82, v86, v83
	v_mul_f32_e32 v83, v85, v85
	v_fmac_f32_e32 v83, v84, v84
	v_add_f32_e32 v82, v83, v82
	v_add_f32_e32 v82, v102, v82
	ds_swizzle_b32 v83, v82 offset:swizzle(SWAP,16)
	v_cvt_pk_bf16_f32 v91, v88, v89
	v_cvt_pk_bf16_f32 v93, v84, v85
	global_store_dwordx4 v[106:107], v[90:93], off offset:256 sc1
	s_waitcnt lgkmcnt(0)
	v_add_f32_e32 v82, v82, v83
	v_mov_b32_e32 v83, v82
	s_nop 1
	v_permlane32_swap_b32_e32 v82, v83
	s_and_saveexec_b64 s[34:35], s[4:5]
	s_cbranch_execz .LBB0_959
	v_lshlrev_b64 v[84:85], 6, v[98:99]
	v_lshl_add_u64 v[84:85], s[40:41], 0, v[84:85]
	v_lshl_add_u64 v[84:85], s[8:9], 2, v[84:85]
	s_lshl_b32 s76, s44, 2
	v_lshl_add_u64 v[84:85], v[84:85], 0, s[76:77]
	v_add_f32_e32 v82, v82, v83
	global_store_dword v[84:85], v82, off
.LBB0_959:
	s_or_b64 exec, exec, s[34:35]
	v_or_b32_e32 v82, 48, v142
	v_ashrrev_i32_e32 v83, 31, v82
	v_lshlrev_b64 v[84:85], 12, v[82:83]
	v_lshl_add_u64 v[84:85], s[12:13], 0, v[84:85]
	v_lshl_add_u64 v[84:85], v[140:141], 2, v[84:85]
	global_load_dwordx4 v[86:89], v[84:85], off offset:16
	global_load_dwordx4 v[90:93], v[84:85], off
	s_waitcnt vmcnt(1)
	v_pk_add_f32 v[76:77], v[76:77], v[88:89]
	s_waitcnt vmcnt(0)
	v_pk_add_f32 v[80:81], v[80:81], v[92:93]
	v_pk_add_f32 v[78:79], v[78:79], v[90:91]
	v_pk_add_f32 v[74:75], v[74:75], v[86:87]
	global_store_dwordx4 v[84:85], v[78:81], off
	global_store_dwordx4 v[84:85], v[74:77], off offset:16
	v_cvt_pk_bf16_f32 v86, v78, v79
	v_mul_f32_e32 v79, v79, v79
	v_fmac_f32_e32 v79, v78, v78
	v_mul_f32_e32 v78, v81, v81
	v_cvt_pk_bf16_f32 v88, v74, v75
	v_lshlrev_b64 v[90:91], 11, v[82:83]
	v_fmac_f32_e32 v78, v80, v80
	v_mul_f32_e32 v75, v75, v75
	v_lshl_add_u64 v[90:91], s[18:19], 0, v[90:91]
	v_add_f32_e32 v78, v79, v78
	v_fmac_f32_e32 v75, v74, v74
	v_cvt_pk_bf16_f32 v87, v80, v81
	v_cvt_pk_bf16_f32 v89, v76, v77
	v_lshl_add_u64 v[90:91], v[140:141], 1, v[90:91]
	v_add_f32_e32 v74, v78, v75
	v_mul_f32_e32 v75, v77, v77
	global_store_dwordx4 v[90:91], v[86:89], off sc1
	v_fmac_f32_e32 v75, v76, v76
	s_nop 0
	v_add_f32_e32 v86, v75, v74
	global_load_dwordx4 v[74:77], v[84:85], off offset:528
	global_load_dwordx4 v[78:81], v[84:85], off offset:512
	s_waitcnt vmcnt(1)
	v_pk_add_f32 v[68:69], v[68:69], v[76:77]
	s_waitcnt vmcnt(0)
	v_pk_add_f32 v[72:73], v[72:73], v[80:81]
	v_pk_add_f32 v[70:71], v[70:71], v[78:79]
	v_pk_add_f32 v[66:67], v[66:67], v[74:75]
	global_store_dwordx4 v[84:85], v[70:73], off offset:512
	global_store_dwordx4 v[84:85], v[66:69], off offset:528
	v_cvt_pk_bf16_f32 v74, v70, v71
	v_mul_f32_e32 v71, v71, v71
	v_fmac_f32_e32 v71, v70, v70
	v_mul_f32_e32 v70, v73, v73
	v_cvt_pk_bf16_f32 v76, v66, v67
	v_fmac_f32_e32 v70, v72, v72
	v_mul_f32_e32 v67, v67, v67
	v_add_f32_e32 v70, v71, v70
	v_fmac_f32_e32 v67, v66, v66
	v_add_f32_e32 v66, v70, v67
	v_mul_f32_e32 v67, v69, v69
	v_fmac_f32_e32 v67, v68, v68
	v_add_f32_e32 v66, v67, v66
	v_add_f32_e32 v66, v86, v66
	ds_swizzle_b32 v67, v66 offset:swizzle(SWAP,16)
	v_cvt_pk_bf16_f32 v75, v72, v73
	v_cvt_pk_bf16_f32 v77, v68, v69
	global_store_dwordx4 v[90:91], v[74:77], off offset:256 sc1
	s_waitcnt lgkmcnt(0)
	v_add_f32_e32 v66, v66, v67
	v_mov_b32_e32 v67, v66
	s_nop 1
	v_permlane32_swap_b32_e32 v66, v67
	s_and_saveexec_b64 s[34:35], s[4:5]
	s_cbranch_execz .LBB0_961
	v_lshlrev_b64 v[68:69], 6, v[82:83]
	v_lshl_add_u64 v[68:69], s[40:41], 0, v[68:69]
	v_lshl_add_u64 v[68:69], s[8:9], 2, v[68:69]
	s_lshl_b32 s76, s44, 2
	v_lshl_add_u64 v[68:69], v[68:69], 0, s[76:77]
	v_add_f32_e32 v66, v66, v67
	global_store_dword v[68:69], v66, off
.LBB0_961:
	s_or_b64 exec, exec, s[34:35]
	v_add_u32_e32 v66, 0x80, v142
	v_ashrrev_i32_e32 v67, 31, v66
	v_lshlrev_b64 v[68:69], 12, v[66:67]
	v_lshl_add_u64 v[68:69], s[12:13], 0, v[68:69]
	v_lshl_add_u64 v[68:69], v[140:141], 2, v[68:69]
	global_load_dwordx4 v[70:73], v[68:69], off offset:16
	global_load_dwordx4 v[74:77], v[68:69], off
	s_waitcnt vmcnt(1)
	v_pk_add_f32 v[60:61], v[60:61], v[72:73]
	s_waitcnt vmcnt(0)
	v_pk_add_f32 v[64:65], v[64:65], v[76:77]
	v_pk_add_f32 v[62:63], v[62:63], v[74:75]
	v_pk_add_f32 v[58:59], v[58:59], v[70:71]
	global_store_dwordx4 v[68:69], v[62:65], off
	global_store_dwordx4 v[68:69], v[58:61], off offset:16
	v_cvt_pk_bf16_f32 v70, v62, v63
	v_mul_f32_e32 v63, v63, v63
	v_fmac_f32_e32 v63, v62, v62
	v_mul_f32_e32 v62, v65, v65
	v_cvt_pk_bf16_f32 v72, v58, v59
	v_lshlrev_b64 v[74:75], 11, v[66:67]
	v_fmac_f32_e32 v62, v64, v64
	v_mul_f32_e32 v59, v59, v59
	v_lshl_add_u64 v[74:75], s[18:19], 0, v[74:75]
	v_add_f32_e32 v62, v63, v62
	v_fmac_f32_e32 v59, v58, v58
	v_cvt_pk_bf16_f32 v71, v64, v65
	v_cvt_pk_bf16_f32 v73, v60, v61
	v_lshl_add_u64 v[74:75], v[140:141], 1, v[74:75]
	v_add_f32_e32 v58, v62, v59
	v_mul_f32_e32 v59, v61, v61
	global_store_dwordx4 v[74:75], v[70:73], off sc1
	v_fmac_f32_e32 v59, v60, v60
	s_nop 0
	v_add_f32_e32 v70, v59, v58
	global_load_dwordx4 v[58:61], v[68:69], off offset:528
	global_load_dwordx4 v[62:65], v[68:69], off offset:512
	s_waitcnt vmcnt(1)
	v_pk_add_f32 v[52:53], v[52:53], v[60:61]
	s_waitcnt vmcnt(0)
	v_pk_add_f32 v[56:57], v[56:57], v[64:65]
	v_pk_add_f32 v[54:55], v[54:55], v[62:63]
	v_pk_add_f32 v[50:51], v[50:51], v[58:59]
	global_store_dwordx4 v[68:69], v[54:57], off offset:512
	global_store_dwordx4 v[68:69], v[50:53], off offset:528
	v_cvt_pk_bf16_f32 v58, v54, v55
	v_mul_f32_e32 v55, v55, v55
	v_fmac_f32_e32 v55, v54, v54
	v_mul_f32_e32 v54, v57, v57
	v_cvt_pk_bf16_f32 v60, v50, v51
	v_fmac_f32_e32 v54, v56, v56
	v_mul_f32_e32 v51, v51, v51
	v_add_f32_e32 v54, v55, v54
	v_fmac_f32_e32 v51, v50, v50
	v_add_f32_e32 v50, v54, v51
	v_mul_f32_e32 v51, v53, v53
	v_fmac_f32_e32 v51, v52, v52
	v_add_f32_e32 v50, v51, v50
	v_add_f32_e32 v50, v70, v50
	ds_swizzle_b32 v51, v50 offset:swizzle(SWAP,16)
	v_cvt_pk_bf16_f32 v59, v56, v57
	v_cvt_pk_bf16_f32 v61, v52, v53
	global_store_dwordx4 v[74:75], v[58:61], off offset:256 sc1
	s_waitcnt lgkmcnt(0)
	v_add_f32_e32 v50, v50, v51
	v_mov_b32_e32 v51, v50
	s_nop 1
	v_permlane32_swap_b32_e32 v50, v51
	s_and_saveexec_b64 s[34:35], s[4:5]
	s_cbranch_execz .LBB0_963
	v_lshlrev_b64 v[52:53], 6, v[66:67]
	v_lshl_add_u64 v[52:53], s[40:41], 0, v[52:53]
	v_lshl_add_u64 v[52:53], s[8:9], 2, v[52:53]
	s_lshl_b32 s76, s44, 2
	v_lshl_add_u64 v[52:53], v[52:53], 0, s[76:77]
	v_add_f32_e32 v50, v50, v51
	global_store_dword v[52:53], v50, off
.LBB0_963:
	s_or_b64 exec, exec, s[34:35]
	v_add_u32_e32 v50, 0x90, v142
	v_ashrrev_i32_e32 v51, 31, v50
	v_lshlrev_b64 v[52:53], 12, v[50:51]
	v_lshl_add_u64 v[52:53], s[12:13], 0, v[52:53]
	v_lshl_add_u64 v[52:53], v[140:141], 2, v[52:53]
	global_load_dwordx4 v[54:57], v[52:53], off offset:16
	global_load_dwordx4 v[58:61], v[52:53], off
	s_waitcnt vmcnt(1)
	v_pk_add_f32 v[44:45], v[44:45], v[56:57]
	s_waitcnt vmcnt(0)
	v_pk_add_f32 v[48:49], v[48:49], v[60:61]
	v_pk_add_f32 v[46:47], v[46:47], v[58:59]
	v_pk_add_f32 v[42:43], v[42:43], v[54:55]
	global_store_dwordx4 v[52:53], v[46:49], off
	global_store_dwordx4 v[52:53], v[42:45], off offset:16
	v_cvt_pk_bf16_f32 v54, v46, v47
	v_mul_f32_e32 v47, v47, v47
	v_fmac_f32_e32 v47, v46, v46
	v_mul_f32_e32 v46, v49, v49
	v_cvt_pk_bf16_f32 v56, v42, v43
	v_lshlrev_b64 v[58:59], 11, v[50:51]
	v_fmac_f32_e32 v46, v48, v48
	v_mul_f32_e32 v43, v43, v43
	v_lshl_add_u64 v[58:59], s[18:19], 0, v[58:59]
	v_add_f32_e32 v46, v47, v46
	v_fmac_f32_e32 v43, v42, v42
	v_cvt_pk_bf16_f32 v55, v48, v49
	v_cvt_pk_bf16_f32 v57, v44, v45
	v_lshl_add_u64 v[58:59], v[140:141], 1, v[58:59]
	v_add_f32_e32 v42, v46, v43
	v_mul_f32_e32 v43, v45, v45
	global_store_dwordx4 v[58:59], v[54:57], off sc1
	v_fmac_f32_e32 v43, v44, v44
	s_nop 0
	v_add_f32_e32 v54, v43, v42
	global_load_dwordx4 v[42:45], v[52:53], off offset:528
	global_load_dwordx4 v[46:49], v[52:53], off offset:512
	s_waitcnt vmcnt(1)
	v_pk_add_f32 v[36:37], v[36:37], v[44:45]
	s_waitcnt vmcnt(0)
	v_pk_add_f32 v[40:41], v[40:41], v[48:49]
	v_pk_add_f32 v[38:39], v[38:39], v[46:47]
	v_pk_add_f32 v[34:35], v[34:35], v[42:43]
	global_store_dwordx4 v[52:53], v[38:41], off offset:512
	global_store_dwordx4 v[52:53], v[34:37], off offset:528
	v_cvt_pk_bf16_f32 v42, v38, v39
	v_mul_f32_e32 v39, v39, v39
	v_fmac_f32_e32 v39, v38, v38
	v_mul_f32_e32 v38, v41, v41
	v_cvt_pk_bf16_f32 v44, v34, v35
	v_fmac_f32_e32 v38, v40, v40
	v_mul_f32_e32 v35, v35, v35
	v_add_f32_e32 v38, v39, v38
	v_fmac_f32_e32 v35, v34, v34
	v_add_f32_e32 v34, v38, v35
	v_mul_f32_e32 v35, v37, v37
	v_fmac_f32_e32 v35, v36, v36
	v_add_f32_e32 v34, v35, v34
	v_add_f32_e32 v34, v54, v34
	ds_swizzle_b32 v35, v34 offset:swizzle(SWAP,16)
	v_cvt_pk_bf16_f32 v43, v40, v41
	v_cvt_pk_bf16_f32 v45, v36, v37
	global_store_dwordx4 v[58:59], v[42:45], off offset:256 sc1
	s_waitcnt lgkmcnt(0)
	v_add_f32_e32 v34, v34, v35
	v_mov_b32_e32 v35, v34
	s_nop 1
	v_permlane32_swap_b32_e32 v34, v35
	s_and_saveexec_b64 s[34:35], s[4:5]
	s_cbranch_execz .LBB0_965
	v_lshlrev_b64 v[36:37], 6, v[50:51]
	v_lshl_add_u64 v[36:37], s[40:41], 0, v[36:37]
	v_lshl_add_u64 v[36:37], s[8:9], 2, v[36:37]
	s_lshl_b32 s76, s44, 2
	v_lshl_add_u64 v[36:37], v[36:37], 0, s[76:77]
	v_add_f32_e32 v34, v34, v35
	global_store_dword v[36:37], v34, off
.LBB0_965:
	s_or_b64 exec, exec, s[34:35]
	v_add_u32_e32 v34, 0xa0, v142
	v_ashrrev_i32_e32 v35, 31, v34
	v_lshlrev_b64 v[36:37], 12, v[34:35]
	v_lshl_add_u64 v[36:37], s[12:13], 0, v[36:37]
	v_lshl_add_u64 v[36:37], v[140:141], 2, v[36:37]
	global_load_dwordx4 v[38:41], v[36:37], off offset:16
	global_load_dwordx4 v[42:45], v[36:37], off
	s_waitcnt vmcnt(1)
	v_pk_add_f32 v[28:29], v[28:29], v[40:41]
	s_waitcnt vmcnt(0)
	v_pk_add_f32 v[32:33], v[32:33], v[44:45]
	v_pk_add_f32 v[30:31], v[30:31], v[42:43]
	v_pk_add_f32 v[26:27], v[26:27], v[38:39]
	global_store_dwordx4 v[36:37], v[30:33], off
	global_store_dwordx4 v[36:37], v[26:29], off offset:16
	v_cvt_pk_bf16_f32 v38, v30, v31
	v_mul_f32_e32 v31, v31, v31
	v_fmac_f32_e32 v31, v30, v30
	v_mul_f32_e32 v30, v33, v33
	v_cvt_pk_bf16_f32 v40, v26, v27
	v_lshlrev_b64 v[42:43], 11, v[34:35]
	v_fmac_f32_e32 v30, v32, v32
	v_mul_f32_e32 v27, v27, v27
	v_lshl_add_u64 v[42:43], s[18:19], 0, v[42:43]
	v_add_f32_e32 v30, v31, v30
	v_fmac_f32_e32 v27, v26, v26
	v_cvt_pk_bf16_f32 v39, v32, v33
	v_cvt_pk_bf16_f32 v41, v28, v29
	v_lshl_add_u64 v[42:43], v[140:141], 1, v[42:43]
	v_add_f32_e32 v26, v30, v27
	v_mul_f32_e32 v27, v29, v29
	global_store_dwordx4 v[42:43], v[38:41], off sc1
	v_fmac_f32_e32 v27, v28, v28
	s_nop 0
	v_add_f32_e32 v38, v27, v26
	global_load_dwordx4 v[26:29], v[36:37], off offset:528
	global_load_dwordx4 v[30:33], v[36:37], off offset:512
	s_waitcnt vmcnt(1)
	v_pk_add_f32 v[20:21], v[20:21], v[28:29]
	s_waitcnt vmcnt(0)
	v_pk_add_f32 v[24:25], v[24:25], v[32:33]
	v_pk_add_f32 v[22:23], v[22:23], v[30:31]
	v_pk_add_f32 v[18:19], v[18:19], v[26:27]
	global_store_dwordx4 v[36:37], v[22:25], off offset:512
	global_store_dwordx4 v[36:37], v[18:21], off offset:528
	v_cvt_pk_bf16_f32 v26, v22, v23
	v_mul_f32_e32 v23, v23, v23
	v_fmac_f32_e32 v23, v22, v22
	v_mul_f32_e32 v22, v25, v25
	v_cvt_pk_bf16_f32 v28, v18, v19
	v_fmac_f32_e32 v22, v24, v24
	v_mul_f32_e32 v19, v19, v19
	v_add_f32_e32 v22, v23, v22
	v_fmac_f32_e32 v19, v18, v18
	v_add_f32_e32 v18, v22, v19
	v_mul_f32_e32 v19, v21, v21
	v_fmac_f32_e32 v19, v20, v20
	v_add_f32_e32 v18, v19, v18
	v_add_f32_e32 v18, v38, v18
	ds_swizzle_b32 v19, v18 offset:swizzle(SWAP,16)
	v_cvt_pk_bf16_f32 v27, v24, v25
	v_cvt_pk_bf16_f32 v29, v20, v21
	global_store_dwordx4 v[42:43], v[26:29], off offset:256 sc1
	s_waitcnt lgkmcnt(0)
	v_add_f32_e32 v18, v18, v19
	v_mov_b32_e32 v19, v18
	s_nop 1
	v_permlane32_swap_b32_e32 v18, v19
	s_and_saveexec_b64 s[34:35], s[4:5]
	s_cbranch_execz .LBB0_967
	v_lshlrev_b64 v[20:21], 6, v[34:35]
	v_lshl_add_u64 v[20:21], s[40:41], 0, v[20:21]
	v_lshl_add_u64 v[20:21], s[8:9], 2, v[20:21]
	s_lshl_b32 s76, s44, 2
	v_lshl_add_u64 v[20:21], v[20:21], 0, s[76:77]
	v_add_f32_e32 v18, v18, v19
	global_store_dword v[20:21], v18, off
.LBB0_967:
	s_or_b64 exec, exec, s[34:35]
	v_add_u32_e32 v18, 0xb0, v142
	v_ashrrev_i32_e32 v19, 31, v18
	v_lshlrev_b64 v[20:21], 12, v[18:19]
	v_lshl_add_u64 v[20:21], s[12:13], 0, v[20:21]
	v_lshl_add_u64 v[20:21], v[140:141], 2, v[20:21]
	global_load_dwordx4 v[22:25], v[20:21], off offset:16
	global_load_dwordx4 v[26:29], v[20:21], off
	s_waitcnt vmcnt(1)
	v_pk_add_f32 v[12:13], v[12:13], v[24:25]
	s_waitcnt vmcnt(0)
	v_pk_add_f32 v[16:17], v[16:17], v[28:29]
	v_pk_add_f32 v[14:15], v[14:15], v[26:27]
	v_pk_add_f32 v[10:11], v[10:11], v[22:23]
	global_store_dwordx4 v[20:21], v[14:17], off
	global_store_dwordx4 v[20:21], v[10:13], off offset:16
	v_cvt_pk_bf16_f32 v22, v14, v15
	v_mul_f32_e32 v15, v15, v15
	v_fmac_f32_e32 v15, v14, v14
	v_mul_f32_e32 v14, v17, v17
	v_cvt_pk_bf16_f32 v24, v10, v11
	v_lshlrev_b64 v[26:27], 11, v[18:19]
	v_fmac_f32_e32 v14, v16, v16
	v_mul_f32_e32 v11, v11, v11
	v_lshl_add_u64 v[26:27], s[18:19], 0, v[26:27]
	v_add_f32_e32 v14, v15, v14
	v_fmac_f32_e32 v11, v10, v10
	v_cvt_pk_bf16_f32 v23, v16, v17
	v_cvt_pk_bf16_f32 v25, v12, v13
	v_lshl_add_u64 v[26:27], v[140:141], 1, v[26:27]
	v_add_f32_e32 v10, v14, v11
	v_mul_f32_e32 v11, v13, v13
	global_store_dwordx4 v[26:27], v[22:25], off sc1
	v_fmac_f32_e32 v11, v12, v12
	s_nop 0
	v_add_f32_e32 v22, v11, v10
	global_load_dwordx4 v[10:13], v[20:21], off offset:528
	global_load_dwordx4 v[14:17], v[20:21], off offset:512
	s_waitcnt vmcnt(1)
	v_pk_add_f32 v[4:5], v[4:5], v[12:13]
	s_waitcnt vmcnt(0)
	v_pk_add_f32 v[8:9], v[8:9], v[16:17]
	v_pk_add_f32 v[6:7], v[6:7], v[14:15]
	v_pk_add_f32 v[2:3], v[2:3], v[10:11]
	global_store_dwordx4 v[20:21], v[6:9], off offset:512
	global_store_dwordx4 v[20:21], v[2:5], off offset:528
	v_cvt_pk_bf16_f32 v10, v6, v7
	v_mul_f32_e32 v7, v7, v7
	v_fmac_f32_e32 v7, v6, v6
	v_mul_f32_e32 v6, v9, v9
	v_cvt_pk_bf16_f32 v12, v2, v3
	v_fmac_f32_e32 v6, v8, v8
	v_mul_f32_e32 v3, v3, v3
	v_add_f32_e32 v6, v7, v6
	v_fmac_f32_e32 v3, v2, v2
	v_add_f32_e32 v2, v6, v3
	v_mul_f32_e32 v3, v5, v5
	v_fmac_f32_e32 v3, v4, v4
	v_add_f32_e32 v2, v3, v2
	v_add_f32_e32 v2, v22, v2
	ds_swizzle_b32 v3, v2 offset:swizzle(SWAP,16)
	v_cvt_pk_bf16_f32 v11, v8, v9
	v_cvt_pk_bf16_f32 v13, v4, v5
	global_store_dwordx4 v[26:27], v[10:13], off offset:256 sc1
	s_waitcnt lgkmcnt(0)
	v_add_f32_e32 v2, v2, v3
	v_mov_b32_e32 v3, v2
	s_nop 1
	v_permlane32_swap_b32_e32 v2, v3
	s_and_saveexec_b64 s[34:35], s[4:5]
	s_cbranch_execz .LBB0_941
	v_lshlrev_b64 v[4:5], 6, v[18:19]
	v_lshl_add_u64 v[4:5], s[40:41], 0, v[4:5]
	v_lshl_add_u64 v[4:5], s[8:9], 2, v[4:5]
	s_lshl_b32 s76, s44, 2
	v_lshl_add_u64 v[4:5], v[4:5], 0, s[76:77]
	v_add_f32_e32 v2, v2, v3
	global_store_dword v[4:5], v2, off
	s_branch .LBB0_941
